# P2 queue fetch: after the first failed claim read all 8 queue heads once and skip atomics on queues already exhausted (one round trip instead of up to 7 sequential probes at the tail)
# baseline (speedup 1.0000x reference)
; DI void phase2(const Params& p, unsigned char* lds) {
;     ...
;         if (tid == 0) {
;             unsigned* heads = (unsigned*)(p.ws + OFF_XBAR + 15360);
;             const unsigned x0 = (unsigned)__builtin_amdgcn_s_getreg((3 << 11) | 20) & 7u;
;             unsigned k = sItem[1], it = 0xffffffffu;
;             while (k < 8u) {
.LBB0_1800:
.LBB0_1801:
	s_and_saveexec_b64 s[4:5], s[40:41]
	s_cbranch_execz .LBB0_1809
	s_mov_b32 s99, 0
	s_mov_b64 s[6:7], src_shared_base
	s_cmp_lg_u32 s42, -1
	s_cselect_b32 s6, s42, 0
	s_cselect_b32 s7, s7, 0
	s_waitcnt vmcnt(0)
	v_mov_b32_e32 v2, s6
	v_mov_b32_e32 v3, s7
	s_getreg_b32 s0, hwreg(HW_REG_XCC_ID, 0, 4)
	ds_read_b32 v3, v2
	s_waitcnt lgkmcnt(0)
	s_mov_b64 s[6:7], 0
	s_branch .LBB0_1804

; DI void phase2(const Params& p, unsigned char* lds) {
;     ...
;             while (k < 8u) {
;                 const unsigned x = (x0 + k) & 7u;
;                 const unsigned got = atomicAdd(heads + x, 1u);
;                 if (got < N_GLA + N_ATT) { it = got | (x << 16); break; }
;                 ++k;
.LBB0_1804:
	s_waitcnt lgkmcnt(0)
	v_mov_b32_e32 v1, v3
	v_cmp_gt_u32_e32 vcc, 8, v1
	s_or_b64 s[10:11], s[10:11], exec
	s_or_b64 s[12:13], s[12:13], exec
	s_and_saveexec_b64 s[14:15], vcc
	s_cbranch_execz .LBB0_1803
	v_add_u32_e32 v2, s0, v1
	v_and_b32_e32 v2, 7, v2
	v_lshlrev_b32_e32 v3, 2, v2
	v_readfirstlane_b32 s16, v2
	s_lshr_b32 s16, s99, s16
	s_bitcmp1_b32 s16, 0
	s_cbranch_scc0 .Lq_try
	v_mov_b32_e32 v4, 0x88
	s_branch .Lq_parked
.Lq_try:
	v_readlane_b32 s16, v236, 63
	s_cmp_eq_u32 s16, -1
	s_cbranch_scc1 .Lq_nopark
	v_mov_b32_e32 v4, s16
	v_writelane_b32 v236, -1, 63
	s_branch .Lq_parked

; DI void phase2(const Params& p, unsigned char* lds) {
;     ...
;                 const unsigned got = atomicAdd(heads + x, 1u);
;                 if (got < N_GLA + N_ATT) { it = got | (x << 16); break; }
;                 ++k;
;             }
;             sItem[1] = k; sItem[0] = it;
.Lq_parked:
	s_movk_i32 s16, 0x88
	s_andn2_b64 s[12:13], s[12:13], exec
	v_add_u32_e32 v3, 1, v1
	s_andn2_b64 s[10:11], s[10:11], exec
	s_waitcnt vmcnt(0)
	v_cmp_gt_u32_e32 vcc, s16, v4
	s_and_b64 s[16:17], vcc, exec
	s_or_b64 s[12:13], s[12:13], s[16:17]
	s_cmp_lg_u64 s[16:17], 0
	s_cbranch_scc1 .Lq_nosnap
	s_cmp_lg_u32 s99, 0
	s_cbranch_scc1 .Lq_nosnap
	v_mov_b32_e32 v248, 0
	global_load_dwordx4 v[240:243], v248, s[58:59] sc0 sc1
	global_load_dwordx4 v[244:247], v248, s[58:59] offset:16 sc0 sc1
	s_waitcnt vmcnt(0)
	v_cmp_lt_u32_e32 vcc, 0x87, v240
	s_and_b32 s17, vcc_lo, 1
	s_or_b32 s99, s99, s17
	v_cmp_lt_u32_e32 vcc, 0x87, v241
	s_and_b32 s17, vcc_lo, 1
	s_lshl_b32 s17, s17, 1
	s_or_b32 s99, s99, s17
	v_cmp_lt_u32_e32 vcc, 0x87, v242
	s_and_b32 s17, vcc_lo, 1
	s_lshl_b32 s17, s17, 2
	s_or_b32 s99, s99, s17
	v_cmp_lt_u32_e32 vcc, 0x87, v243
	s_and_b32 s17, vcc_lo, 1
	s_lshl_b32 s17, s17, 3
	s_or_b32 s99, s99, s17
	v_cmp_lt_u32_e32 vcc, 0x87, v244
	s_and_b32 s17, vcc_lo, 1
	s_lshl_b32 s17, s17, 4
	s_or_b32 s99, s99, s17
	v_cmp_lt_u32_e32 vcc, 0x87, v245
	s_and_b32 s17, vcc_lo, 1
	s_lshl_b32 s17, s17, 5
	s_or_b32 s99, s99, s17
	v_cmp_lt_u32_e32 vcc, 0x87, v246
	s_and_b32 s17, vcc_lo, 1
	s_lshl_b32 s17, s17, 6
	s_or_b32 s99, s99, s17
	v_cmp_lt_u32_e32 vcc, 0x87, v247
	s_and_b32 s17, vcc_lo, 1
	s_lshl_b32 s17, s17, 7
	s_or_b32 s99, s99, s17
.Lq_nosnap:
	s_branch .LBB0_1803
.LBB0_1806:
	s_or_b64 exec, exec, s[6:7]
	s_xor_b64 s[6:7], s[8:9], -1
	v_mov_b32_e32 v3, -1
	s_and_saveexec_b64 s[8:9], s[6:7]
	s_xor_b64 s[6:7], exec, s[8:9]
	v_lshl_or_b32 v3, v2, 16, v4
	s_or_b64 exec, exec, s[6:7]
	s_cmp_lg_u32 s42, -1
	s_mov_b64 s[6:7], src_shared_base
	s_cselect_b32 s0, s42, 0
	s_cselect_b32 s6, s7, 0
	v_mov_b32_e32 v4, s0
	s_add_i32 s0, 0, 0x25000
	s_cmp_lg_u32 s0, -1
	v_mov_b32_e32 v5, s6
	s_cselect_b32 s0, s0, 0
	s_cselect_b32 s6, s7, 0
	ds_write_b32 v4, v1
	v_mov_b32_e32 v4, s0
	v_mov_b32_e32 v5, s6
	ds_write_b32 v4, v3
	s_waitcnt lgkmcnt(0)
